# v43 + member workgroups' barrier poll loop sleeps s_sleep 3 instead of 1 between polls (less polling traffic while tail tiles run)
# speedup vs baseline: 1.0007x; 1.0007x over previous
; __device__ __forceinline__ unsigned xb_ld(unsigned* p)              { return __hip_atomic_load(p, __ATOMIC_RELAXED, __HIP_MEMORY_SCOPE_AGENT); }
; __device__ __forceinline__ unsigned xb_add(unsigned* p, unsigned v) { return __hip_atomic_fetch_add(p, v, __ATOMIC_RELAXED, __HIP_MEMORY_SCOPE_AGENT); }
; #define XB_SPIN(cond, bar) do { unsigned _sp = 0; while (cond) { __builtin_amdgcn_s_sleep(1); \
;     if ((++_sp & 255u) == 0u) { if (xb_ld(&(bar)[XB_TMO])) break; if (_sp > XB_SPIN_CAP) { atomicAdd(&(bar)[XB_TMO], 1u); break; } } } } while (0)
; __device__ __forceinline__ void xcd_barrier(const XcdBarrier& b, int tid_) {
;     ...
;             else XB_SPIN(xb_ld(&bar[XB_TOPGEN]) == tg, bar);
;             __builtin_amdgcn_fence(__ATOMIC_ACQUIRE, "agent");
;             xb_add(&bar[XB_XGEN(b.x)], 1u);
;             asm volatile("s_waitcnt vmcnt(0)" ::: "memory");
;         } else {
;             XB_SPIN(xb_ld(&bar[XB_XGEN(b.x)]) == gen, bar);
.LBB0_984:
	s_and_b32 s15, s2, 0xff
	s_mov_b64 s[12:13], -1
	s_cmp_lg_u32 s15, 0
	s_mov_b64 s[18:19], -1
	s_sleep 3
	s_cbranch_scc0 .LBB0_987
	s_and_b64 vcc, exec, s[18:19]
	s_cbranch_vccz .LBB0_983
